# E41: grid barrier - first and middle arrivers of each XCD issue an early async buffer_wbl2 so the leader's release flush has less to write back
# baseline (speedup 1.0000x reference)
; DI unsigned xb_ld(unsigned* p)              { return __hip_atomic_load(p, __ATOMIC_RELAXED, __HIP_MEMORY_SCOPE_AGENT); }
; DI unsigned xb_add(unsigned* p, unsigned v) { return __hip_atomic_fetch_add(p, v, __ATOMIC_RELAXED, __HIP_MEMORY_SCOPE_AGENT); }
; #define XB_SPIN(cond, bar) do { unsigned _sp = 0; while (cond) { __builtin_amdgcn_s_sleep(1); \
;     if ((++_sp & 255u) == 0u) { if (xb_ld(&(bar)[XB_TMO])) break; if (_sp > XB_SPIN_CAP) { atomicAdd(&(bar)[XB_TMO], 1u); break; } } } } while (0)
; DI void xcd_barrier(const XcdBarrier& b) {
;     ...
;         const unsigned old = xb_add(&bar[XB_XSUB(b.x)], 1u);
;         const unsigned gen = old / nloc;
;         if (old + 1u == (gen + 1u) * nloc) {
;             __builtin_amdgcn_fence(__ATOMIC_RELEASE, "agent");
;             asm volatile("s_waitcnt vmcnt(0)" ::: "memory");
;             const unsigned og = xb_add(&bar[XB_TOP], 1u);
;             const unsigned tg = og / nx;
;             if (og + 1u == (tg + 1u) * nx) xb_add(&bar[XB_TOPGEN], 1u);
;             else XB_SPIN(xb_ld(&bar[XB_TOPGEN]) == tg, bar);
;             __builtin_amdgcn_fence(__ATOMIC_ACQUIRE, "agent");
;             xb_add(&bar[XB_XGEN(b.x)], 1u);
;             asm volatile("s_waitcnt vmcnt(0)" ::: "memory");
;         } else {
;             XB_SPIN(xb_ld(&bar[XB_XGEN(b.x)]) == gen, bar);
.LBB0_58:
	s_lshl_b32 s8, s3, 8
	s_add_u32 s8, s40, s8
	s_addc_u32 s9, s41, 0
	v_mov_b32_e32 v1, 0x1000
	v_mov_b32_e32 v3, 1
	global_atomic_add v3, v1, v3, s[8:9] offset:1024 sc0
	v_cvt_f32_u32_e32 v1, v2
	v_sub_u32_e32 v4, 0, v2
	s_add_u32 s8, s8, 0x2400
	s_addc_u32 s9, s9, 0
	v_rcp_iflag_f32_e32 v1, v1
	s_nop 0
	v_mul_f32_e32 v1, 0x4f7ffffe, v1
	v_cvt_u32_f32_e32 v1, v1
	v_mul_lo_u32 v4, v4, v1
	v_mul_hi_u32 v4, v1, v4
	v_add_u32_e32 v1, v1, v4
	s_waitcnt vmcnt(0)
	v_mul_hi_u32 v1, v3, v1
	v_mul_lo_u32 v4, v1, v2
	v_sub_u32_e32 v4, v3, v4
	v_add_u32_e32 v5, 1, v1
	v_cmp_ge_u32_e32 vcc, v4, v2
	v_add_u32_e32 v3, 1, v3
	s_nop 0
	v_cndmask_b32_e32 v1, v1, v5, vcc
	v_sub_u32_e32 v5, v4, v2
	v_cndmask_b32_e32 v4, v4, v5, vcc
	v_add_u32_e32 v5, 1, v1
	v_cmp_ge_u32_e32 vcc, v4, v2
	s_nop 1
	v_cndmask_b32_e32 v1, v1, v5, vcc
	v_mul_lo_u32 v4, v2, v1
	v_add_u32_e32 v2, v4, v2
	v_cmp_ne_u32_e32 vcc, v3, v2
	s_and_saveexec_b64 s[10:11], vcc
	s_xor_b64 s[10:11], exec, s[10:11]
	s_cbranch_execz .LBB0_72
	v_sub_u32_e32 v3, v3, v4
	v_sub_u32_e32 v4, v2, v4
	v_lshrrev_b32_e32 v4, 1, v4
	v_add_u32_e32 v4, 1, v4
	v_cmp_eq_u32_e32 vcc, 1, v3
	s_cbranch_vccnz .Lxb_flush_1
	v_cmp_ne_u32_e32 vcc, v3, v4
	s_cbranch_vccnz .Lxb_noflush_1
.Lxb_flush_1:
	buffer_wbl2 sc1
.Lxb_noflush_1:
	s_waitcnt lgkmcnt(0)
	v_mov_b32_e32 v0, 0
	global_load_dword v2, v0, s[8:9] sc1
	s_waitcnt vmcnt(0)
	v_cmp_eq_u32_e32 vcc, v2, v1
	s_and_saveexec_b64 s[12:13], vcc
	s_cbranch_execz .LBB0_71
	s_mov_b32 s24, 1
	s_mov_b64 s[14:15], 0
	s_branch .LBB0_62

; DI unsigned xb_ld(unsigned* p)              { return __hip_atomic_load(p, __ATOMIC_RELAXED, __HIP_MEMORY_SCOPE_AGENT); }
; DI unsigned xb_add(unsigned* p, unsigned v) { return __hip_atomic_fetch_add(p, v, __ATOMIC_RELAXED, __HIP_MEMORY_SCOPE_AGENT); }
; #define XB_SPIN(cond, bar) do { unsigned _sp = 0; while (cond) { __builtin_amdgcn_s_sleep(1); \
;     if ((++_sp & 255u) == 0u) { if (xb_ld(&(bar)[XB_TMO])) break; if (_sp > XB_SPIN_CAP) { atomicAdd(&(bar)[XB_TMO], 1u); break; } } } } while (0)
; DI void xcd_barrier(const XcdBarrier& b) {
;     ...
;         const unsigned old = xb_add(&bar[XB_XSUB(b.x)], 1u);
;         const unsigned gen = old / nloc;
;         if (old + 1u == (gen + 1u) * nloc) {
;             __builtin_amdgcn_fence(__ATOMIC_RELEASE, "agent");
;             asm volatile("s_waitcnt vmcnt(0)" ::: "memory");
;             const unsigned og = xb_add(&bar[XB_TOP], 1u);
;             const unsigned tg = og / nx;
;             if (og + 1u == (tg + 1u) * nx) xb_add(&bar[XB_TOPGEN], 1u);
;             else XB_SPIN(xb_ld(&bar[XB_TOPGEN]) == tg, bar);
;             __builtin_amdgcn_fence(__ATOMIC_ACQUIRE, "agent");
;             xb_add(&bar[XB_XGEN(b.x)], 1u);
;             asm volatile("s_waitcnt vmcnt(0)" ::: "memory");
;         } else {
;             XB_SPIN(xb_ld(&bar[XB_XGEN(b.x)]) == gen, bar);
.LBB0_1005:
	v_readlane_b32 s4, v253, 52
	v_readlane_b32 s5, v253, 53
	v_cvt_f32_u32_e32 v1, v2
	v_sub_u32_e32 v4, 0, v2
	v_rcp_iflag_f32_e32 v1, v1
	s_nop 1
	global_atomic_add v3, v173, v237, s[4:5] sc0
	v_mul_f32_e32 v1, 0x4f7ffffe, v1
	v_cvt_u32_f32_e32 v1, v1
	v_mul_lo_u32 v4, v4, v1
	v_mul_hi_u32 v4, v1, v4
	v_add_u32_e32 v1, v1, v4
	s_waitcnt vmcnt(0)
	v_mul_hi_u32 v1, v3, v1
	v_mul_lo_u32 v4, v1, v2
	v_sub_u32_e32 v4, v3, v4
	v_add_u32_e32 v5, 1, v1
	v_cmp_ge_u32_e32 vcc, v4, v2
	v_add_u32_e32 v3, 1, v3
	s_nop 0
	v_cndmask_b32_e32 v1, v1, v5, vcc
	v_sub_u32_e32 v5, v4, v2
	v_cndmask_b32_e32 v4, v4, v5, vcc
	v_add_u32_e32 v5, 1, v1
	v_cmp_ge_u32_e32 vcc, v4, v2
	s_nop 1
	v_cndmask_b32_e32 v1, v1, v5, vcc
	v_mul_lo_u32 v4, v2, v1
	v_add_u32_e32 v2, v4, v2
	v_cmp_ne_u32_e32 vcc, v3, v2
	s_and_saveexec_b64 s[4:5], vcc
	s_xor_b64 s[4:5], exec, s[4:5]
	s_cbranch_execz .LBB0_1019
	v_sub_u32_e32 v3, v3, v4
	v_sub_u32_e32 v4, v2, v4
	v_lshrrev_b32_e32 v4, 1, v4
	v_add_u32_e32 v4, 1, v4
	v_cmp_eq_u32_e32 vcc, 1, v3
	s_cbranch_vccnz .Lxb_flush_4
	v_cmp_ne_u32_e32 vcc, v3, v4
	s_cbranch_vccnz .Lxb_noflush_4

; DI unsigned xb_ld(unsigned* p)              { return __hip_atomic_load(p, __ATOMIC_RELAXED, __HIP_MEMORY_SCOPE_AGENT); }
; #define XB_SPIN(cond, bar) do { unsigned _sp = 0; while (cond) { __builtin_amdgcn_s_sleep(1); \
;     if ((++_sp & 255u) == 0u) { if (xb_ld(&(bar)[XB_TMO])) break; if (_sp > XB_SPIN_CAP) { atomicAdd(&(bar)[XB_TMO], 1u); break; } } } } while (0)
; DI void xcd_barrier(const XcdBarrier& b) {
;     ...
;             XB_SPIN(xb_ld(&bar[XB_XGEN(b.x)]) == gen, bar);
;             __builtin_amdgcn_fence(__ATOMIC_ACQUIRE, "agent");
;             asm volatile("s_waitcnt vmcnt(0)" ::: "memory");
.Lxb_noflush_4:
	v_readlane_b32 s6, v253, 54
	v_readlane_b32 s7, v253, 55
	s_waitcnt lgkmcnt(0)
	s_nop 3
	global_load_dword v0, v173, s[6:7] sc1
	s_waitcnt vmcnt(0)
	v_cmp_eq_u32_e32 vcc, v0, v1
	s_and_saveexec_b64 s[6:7], vcc
	s_cbranch_execz .LBB0_1018
	s_mov_b32 s18, 1
	s_mov_b64 s[8:9], 0
	s_branch .LBB0_1009
